# MLA tile loop: K/V staging pointers pre-selected per lane with per-lane strides (no per-tile pointer select / base add), on top of v12
# speedup vs baseline: 1.0045x; 1.0045x over previous
; __device__ __forceinline__ void mla_attn_phase(const Ctx&, unsigned char* ws) { const Ctx c = mk_ctx();
;     ...
;         f32x16 oa[2]; oa[0] = f32x16{}; oa[1] = f32x16{}; float mrun = -INFINITY, lrun = 0.f;
;         v4u kreg0, kreg1 = {0u, 0u, 0u, 0u}, vreg;
;     ...
;         MLA_LOAD(0);
;         for (int j = 0; j < ntiles; ++j) { bf16* Kb = Kl + (j & 1) * KTILE_E; bf16* Vb = Vl + (j & 1) * VTILE_E;
;             *(v4u*)(Kb + kc0_row * KLD + kc0_part * 8) = kreg0; if (tid < 256) *(v4u*)(Kb + kc1_row * KLD + kc1_part * 8) = kreg1;
;             *(v2u*)(Vb + vd * VLD + vpart * 8) = (v2u){vreg.x, vreg.y}; *(v2u*)(Vb + vd * VLD + vpart * 8 + 4) = (v2u){vreg.z, vreg.w};
;             __syncthreads();
;             if (j + 1 < ntiles) MLA_LOAD(j + 1);
.LBB0_744:
	s_or_b64 exec, exec, s[24:25]
	s_lshl_b32 s24, s37, 3
	s_and_b32 s24, s24, 0x7c0
	v_add_u32_e32 v2, s24, v1
	v_ashrrev_i32_e32 v3, 31, v2
	v_lshlrev_b64 v[2:3], 14, v[2:3]
	v_lshl_add_u64 v[4:5], v[122:123], 0, v[2:3]
	global_load_dwordx4 v[98:101], v[4:5], off
	s_add_i32 s24, s38, 0x100
	s_lshr_b32 s35, s24, 6
	s_lshr_b32 s24, s36, 26
	s_add_i32 s24, s24, s34
	s_add_i32 s24, s24, 31
	s_ashr_i32 s36, s24, 6
	s_lshr_b32 s24, s37, 7
	s_lshl_b32 s26, s37, 4
	s_lshl_b32 s25, s24, 24
	s_and_b32 s26, s26, 0x780
	v_mov_b32_e32 v18, v151
	v_mov_b32_e32 v19, v151
	v_lshl_add_u64 v[136:137], v[124:125], 0, v[2:3]
	s_or_b32 s96, s26, s25
	s_lshl_b32 s24, s24, 19
	s_mov_b32 s25, s97
	v_mov_b32_e32 v20, v151
	v_mov_b32_e32 v21, v151
	v_mov_b32_e32 v22, v151
	v_mov_b32_e32 v23, v151
	v_mov_b32_e32 v24, v151
	v_mov_b32_e32 v25, v151
	v_mov_b32_e32 v26, v151
	v_mov_b32_e32 v27, v151
	v_mov_b32_e32 v28, v151
	v_mov_b32_e32 v29, v151
	v_mov_b32_e32 v30, v151
	v_mov_b32_e32 v31, v151
	v_mov_b32_e32 v32, v151
	v_mov_b32_e32 v33, v151
	v_mov_b64_e32 v[2:3], v[18:19]
	v_add_u32_e32 v187, s38, v186
	v_lshl_add_u64 v[138:139], s[96:97], 0, v[126:127]
	v_lshl_add_u64 v[140:141], v[128:129], 0, s[24:25]
	v_lshl_add_u64 v[142:143], s[96:97], 0, v[130:131]
	v_lshl_add_u64 v[144:145], v[132:133], 0, s[24:25]
	s_mov_b32 s41, 0
	v_mov_b32_e32 v189, 0
	v_cmp_gt_u32_e32 vcc, 32, v206
	v_mov_b32_e32 v246, 0xbf80
	v_mov_b32_e32 v247, 0
	v_cndmask_b32_e32 v246, 0, v246, vcc
	v_mov_b32_e32 v252, 0
	v_mov_b32_e32 v253, 0
	v_mov_b32_e32 v188, 0
	s_mov_b32 s37, 63
	v_mov_b64_e32 v[4:5], v[20:21]
	v_mov_b64_e32 v[6:7], v[22:23]
	v_mov_b64_e32 v[8:9], v[24:25]
	v_mov_b64_e32 v[10:11], v[26:27]
	v_mov_b64_e32 v[12:13], v[28:29]
	v_mov_b64_e32 v[14:15], v[30:31]
	v_mov_b64_e32 v[16:17], v[32:33]
	v_lshl_add_u64 v[34:35], s[0:1], 0, v[142:143]
	v_lshl_add_u64 v[36:37], s[0:1], 0, v[144:145]
	v_mov_b32_e32 v190, 0x1000
	v_mov_b32_e32 v191, 0x20000
	v_cndmask_b32_e64 v143, v37, v35, s[4:5]
	v_cndmask_b32_e64 v142, v36, v34, s[4:5]
	v_cndmask_b32_e64 v144, v190, v191, s[4:5]
	v_mov_b32_e32 v145, 0
	v_lshl_add_u64 v[34:35], s[0:1], 0, v[138:139]
	v_lshl_add_u64 v[36:37], s[0:1], 0, v[140:141]
	v_cndmask_b32_e64 v139, v37, v35, s[10:11]
	v_cndmask_b32_e64 v138, v36, v34, s[10:11]
	v_cndmask_b32_e64 v140, v190, v191, s[10:11]
	v_mov_b32_e32 v141, 0
	v_lshl_add_u64 v[136:137], s[0:1], 0, v[136:137]
.LBB0_745:
	s_and_b32 s26, s41, 1
	s_mul_i32 s24, s26, 0x3400
	s_add_i32 s43, s24, 0
	v_lshlrev_b32_e32 v34, 1, v112
	v_add3_u32 v34, s43, v103, v34
	s_waitcnt vmcnt(1)
	ds_write_b128 v34, v[90:93]
	s_and_saveexec_b64 s[24:25], s[8:9]
	v_add3_u32 v34, s43, v119, v154
	ds_write_b128 v34, v[94:97]
	s_or_b64 exec, exec, s[24:25]
	s_mulk_i32 s26, 0xee00
	s_add_i32 s39, s43, s26
	s_add_i32 s38, s41, 1
	v_add_u32_e32 v34, s39, v109
	s_movk_i32 s24, 0x6800
	s_cmp_ge_u32 s38, s35
	v_add3_u32 v34, v34, v120, s24
	s_cselect_b64 s[24:25], -1, 0
	s_and_b64 vcc, exec, s[24:25]
	s_waitcnt vmcnt(0)
	ds_write2_b64 v34, v[98:99], v[100:101] offset1:1
	s_waitcnt lgkmcnt(0)
	s_barrier
	s_cbranch_vccnz .LBB0_751
	global_load_dwordx4 v[90:93], v[142:143], off
	s_and_saveexec_b64 s[26:27], s[8:9]
	s_cbranch_execz .LBB0_750
	global_load_dwordx4 v[94:97], v[138:139], off
.LBB0_750:
	s_or_b64 exec, exec, s[26:27]
	global_load_dwordx4 v[98:101], v[136:137], off

; __device__ __forceinline__ void mla_attn_phase(const Ctx&, unsigned char* ws) { const Ctx c = mk_ctx();
;     ...
;         MLA_LOAD(0);
;         for (int j = 0; j < ntiles; ++j) { bf16* Kb = Kl + (j & 1) * KTILE_E; bf16* Vb = Vl + (j & 1) * VTILE_E;
.LBB0_755:
	v_subrev_u32_e32 v187, 64, v187
	s_add_i32 s37, s37, 64
	v_lshl_add_u64 v[136:137], v[136:137], 0, s[94:95]
	v_lshl_add_u64 v[138:139], v[138:139], 0, v[140:141]
	v_lshl_add_u64 v[142:143], v[142:143], 0, v[144:145]
	s_and_b64 vcc, exec, s[24:25]
	s_cbranch_vccnz .LBB0_727
	s_mov_b32 s41, s38
	s_branch .LBB0_745
